# speedup vs baseline: 1.0141x; 1.0141x over previous
; __device__ __forceinline__ float bf2f(bf16_t h) { return __uint_as_float(((unsigned)h) << 16); }
; __device__ __forceinline__ void rowpass_resid(const Params& p, const float* __restrict__ ga, const float* __restrict__ gb, bool write_xn, bool from_x = false) {
;     ...
;     for (int row = blockIdx.x * 8 + w; row < T; row += gridDim.x * 8) {
;         float* hp = hrow(p, row);
;         const float* hsrc = hp;
;         if (from_x) { const int b_ = row / L, pos_ = row - b_ * L; if (pos_ >= NMETA) hsrc = p.in[0] + ((size_t)b_ * SEQ + pos_ - NMETA) * DM; }
;         bf16_t* xp = XU + (size_t)row * DM;
;         float u[16]; float ss = 0.f;
; #pragma unroll
;         for (int i = 0; i < 4; ++i) {
;             uint2 q = *(const uint2*)(xp + lane * 4 + 256 * i);
;             u[4 * i + 0] = bf2f((bf16_t)(q.x & 0xFFFF)); u[4 * i + 1] = bf2f((bf16_t)(q.x >> 16));
;             u[4 * i + 2] = bf2f((bf16_t)(q.y & 0xFFFF)); u[4 * i + 3] = bf2f((bf16_t)(q.y >> 16));
; #pragma unroll
;             for (int j = 0; j < 4; ++j) ss += u[4 * i + j] * u[4 * i + j];
;         }
;         ss = wave_sum(ss);
;         float r = rsqrtf(ss * (1.0f / DM) + EPS);
;         float hv[16]; float s2 = 0.f;
; #pragma unroll
;         for (int i = 0; i < 4; ++i) {
;             float4 h4 = *(const float4*)(hsrc + lane * 4 + 256 * i);
;             float4 g4 = *(const float4*)(ga + lane * 4 + 256 * i);
;             hv[4 * i + 0] = h4.x + u[4 * i + 0] * r * g4.x;
;             hv[4 * i + 1] = h4.y + u[4 * i + 1] * r * g4.y;
;             hv[4 * i + 2] = h4.z + u[4 * i + 2] * r * g4.z;
;             hv[4 * i + 3] = h4.w + u[4 * i + 3] * r * g4.w;
;             *(float4*)(hp + lane * 4 + 256 * i) = make_float4(hv[4 * i], hv[4 * i + 1], hv[4 * i + 2], hv[4 * i + 3]);
; #pragma unroll
;             for (int j = 0; j < 4; ++j) s2 += hv[4 * i + j] * hv[4 * i + j];
.LBB0_977:
	s_or_b64 exec, exec, s[8:9]
	v_readlane_b32 s68, v252, 4
	v_readlane_b32 s69, v252, 5
	v_lshlrev_b64 v[44:45], 12, v[0:1]
	s_mov_b32 s8, 0xffff0000
	v_lshl_add_u64 v[40:41], s[68:69], 0, v[40:41]
	v_lshlrev_b64 v[42:43], 12, v[42:43]
	v_cmp_lt_i32_e32 vcc, 15, v0
	v_lshl_add_u64 v[40:41], v[40:41], 0, v[44:45]
	s_mov_b32 s9, -1
	v_lshl_add_u64 v[42:43], v[46:47], 0, v[42:43]
	s_and_b64 vcc, s[2:3], vcc
	v_lshl_add_u64 v[40:41], v[40:41], 0, s[8:9]
	v_ashrrev_i32_e32 v35, 31, v34
	v_cndmask_b32_e32 v45, v43, v41, vcc
	v_cndmask_b32_e32 v44, v42, v40, vcc
	v_lshlrev_b64 v[40:41], 11, v[34:35]
	v_lshl_add_u64 v[40:41], v[36:37], 0, v[40:41]
	global_load_dwordx2 v[88:89], v[40:41], off
	global_load_dwordx2 v[90:91], v[40:41], off offset:512
	global_load_dwordx2 v[92:93], v[40:41], off offset:1024
	global_load_dwordx2 v[94:95], v[40:41], off offset:1536
	v_mov_b32_e32 v39, v1
	v_lshl_add_u64 v[70:71], v[44:45], 0, v[38:39]
	v_lshl_add_u64 v[72:73], v[42:43], 0, v[38:39]
	global_load_dwordx4 v[42:45], v[70:71], off
	global_load_dwordx4 v[96:99], v[70:71], off offset:1024
	global_load_dwordx4 v[100:103], v[70:71], off offset:2048
	global_load_dwordx4 v[104:107], v[70:71], off offset:3072
	s_mov_b32 s8, 0x800000
	v_add_u32_e32 v34, s66, v34
	s_waitcnt vmcnt(4)
	v_lshlrev_b32_e32 v54, 16, v88
	v_and_b32_e32 v55, 0xffff0000, v88
	v_lshlrev_b32_e32 v46, 16, v89
	v_and_b32_e32 v47, 0xffff0000, v89
	v_lshlrev_b32_e32 v58, 16, v90
	v_and_b32_e32 v59, 0xffff0000, v90
	v_lshlrev_b32_e32 v60, 16, v91
	v_and_b32_e32 v61, 0xffff0000, v91
	v_lshlrev_b32_e32 v62, 16, v92
	v_and_b32_e32 v63, 0xffff0000, v92
	v_lshlrev_b32_e32 v64, 16, v93
	v_and_b32_e32 v65, 0xffff0000, v93
	v_lshlrev_b32_e32 v66, 16, v94
	v_and_b32_e32 v67, 0xffff0000, v94
	v_lshlrev_b32_e32 v68, 16, v95
	v_and_b32_e32 v69, 0xffff0000, v95
	v_pk_mul_f32 v[74:75], v[46:47], v[46:47]
	v_pk_mul_f32 v[76:77], v[58:59], v[58:59]
	v_pk_mul_f32 v[78:79], v[60:61], v[60:61]
	v_pk_mul_f32 v[80:81], v[62:63], v[62:63]
	v_pk_mul_f32 v[82:83], v[64:65], v[64:65]
	v_pk_mul_f32 v[56:57], v[54:55], v[54:55]
	v_pk_mul_f32 v[84:85], v[66:67], v[66:67]
	v_add_f32_e32 v0, v56, v57
	v_add_f32_e32 v0, v0, v74
	v_add_f32_e32 v0, v75, v0
	v_add_f32_e32 v0, v76, v0
	v_add_f32_e32 v0, v77, v0
	v_add_f32_e32 v0, v78, v0
	v_add_f32_e32 v0, v79, v0
	v_add_f32_e32 v0, v80, v0
	v_add_f32_e32 v0, v81, v0
	v_add_f32_e32 v0, v82, v0
	v_add_f32_e32 v0, v83, v0
	v_add_f32_e32 v0, v84, v0
	v_pk_mul_f32 v[86:87], v[68:69], v[68:69]
	v_add_f32_e32 v0, v85, v0
	v_add_f32_e32 v0, v86, v0
	v_add_f32_e32 v0, v87, v0
	ds_bpermute_b32 v35, v48, v0
	s_waitcnt lgkmcnt(0)
	v_add_f32_e32 v0, v0, v35
	ds_bpermute_b32 v35, v49, v0
	s_waitcnt lgkmcnt(0)
	v_add_f32_e32 v0, v0, v35
	ds_bpermute_b32 v35, v50, v0
	s_waitcnt lgkmcnt(0)
	v_add_f32_e32 v0, v0, v35
	ds_bpermute_b32 v35, v51, v0
	s_waitcnt lgkmcnt(0)
	v_add_f32_e32 v0, v0, v35
	ds_bpermute_b32 v35, v52, v0
	s_waitcnt lgkmcnt(0)
	v_add_f32_e32 v0, v0, v35
	ds_bpermute_b32 v35, v53, v0
	s_waitcnt lgkmcnt(0)
	v_add_f32_e32 v0, v0, v35
	v_fmamk_f32 v0, v0, 0x3a800000, v174
	v_cmp_gt_f32_e32 vcc, s8, v0
	v_mul_f32_e32 v35, 0x4b800000, v0
	s_nop 0
	v_cndmask_b32_e32 v0, v0, v35, vcc
	v_rsq_f32_e32 v0, v0
	s_nop 0
	v_mul_f32_e32 v35, 0x45800000, v0
	v_cndmask_b32_e32 v0, v0, v35, vcc
	v_pk_mul_f32 v[54:55], v[0:1], v[54:55] op_sel_hi:[0,1]
	v_pk_mul_f32 v[46:47], v[0:1], v[46:47] op_sel_hi:[0,1]
	s_waitcnt vmcnt(3)
	v_pk_fma_f32 v[42:43], v[10:11], v[54:55], v[42:43]
	v_pk_fma_f32 v[44:45], v[12:13], v[46:47], v[44:45]
	global_store_dwordx4 v[72:73], v[42:45], off
	v_pk_mul_f32 v[46:47], v[0:1], v[58:59] op_sel_hi:[0,1]
	s_waitcnt vmcnt(3)
; __device__ __forceinline__ void rowpass_resid(const Params& p, const float* __restrict__ ga, const float* __restrict__ gb, bool write_xn, bool from_x = false) {
;     ...
;         for (int i = 0; i < 4; ++i) {
;             float4 h4 = *(const float4*)(hsrc + lane * 4 + 256 * i);
;             float4 g4 = *(const float4*)(ga + lane * 4 + 256 * i);
;             hv[4 * i + 0] = h4.x + u[4 * i + 0] * r * g4.x;
;             hv[4 * i + 1] = h4.y + u[4 * i + 1] * r * g4.y;
;             hv[4 * i + 2] = h4.z + u[4 * i + 2] * r * g4.z;
;             hv[4 * i + 3] = h4.w + u[4 * i + 3] * r * g4.w;
;             *(float4*)(hp + lane * 4 + 256 * i) = make_float4(hv[4 * i], hv[4 * i + 1], hv[4 * i + 2], hv[4 * i + 3]);
; #pragma unroll
;             for (int j = 0; j < 4; ++j) s2 += hv[4 * i + j] * hv[4 * i + j];
;         }
;         if (write_xn) {
;             s2 = wave_sum(s2);
;             float r2 = rsqrtf(s2 * (1.0f / DM) + EPS);
; #pragma unroll
;             for (int i = 0; i < 4; ++i) {
;                 float4 g4 = *(const float4*)(gb + lane * 4 + 256 * i);
;                 uint2 o; o.x = pack2(hv[4 * i] * r2 * g4.x, hv[4 * i + 1] * r2 * g4.y);
;                 o.y = pack2(hv[4 * i + 2] * r2 * g4.z, hv[4 * i + 3] * r2 * g4.w);
;                 *(uint2*)(xp + lane * 4 + 256 * i) = o;
;             }
;         }
	v_pk_fma_f32 v[96:97], v[2:3], v[46:47], v[96:97]
	v_pk_mul_f32 v[46:47], v[0:1], v[60:61] op_sel_hi:[0,1]
	v_pk_fma_f32 v[98:99], v[4:5], v[46:47], v[98:99]
	global_store_dwordx4 v[72:73], v[96:99], off offset:1024
	v_pk_mul_f32 v[46:47], v[0:1], v[62:63] op_sel_hi:[0,1]
	s_waitcnt vmcnt(3)
	v_pk_fma_f32 v[100:101], v[6:7], v[46:47], v[100:101]
	v_pk_mul_f32 v[46:47], v[0:1], v[64:65] op_sel_hi:[0,1]
	v_pk_fma_f32 v[102:103], v[8:9], v[46:47], v[102:103]
	global_store_dwordx4 v[72:73], v[100:103], off offset:2048
	v_pk_mul_f32 v[46:47], v[0:1], v[66:67] op_sel_hi:[0,1]
	v_pk_mul_f32 v[66:67], v[44:45], v[44:45]
	v_pk_mul_f32 v[70:71], v[98:99], v[98:99]
	v_pk_mul_f32 v[74:75], v[102:103], v[102:103]
	s_waitcnt vmcnt(3)
	v_pk_fma_f32 v[104:105], v[18:19], v[46:47], v[104:105]
	v_pk_mul_f32 v[46:47], v[0:1], v[68:69] op_sel_hi:[0,1]
	v_pk_fma_f32 v[106:107], v[20:21], v[46:47], v[106:107]
	v_pk_mul_f32 v[46:47], v[42:43], v[42:43]
	v_pk_mul_f32 v[68:69], v[96:97], v[96:97]
	v_add_f32_e32 v0, v46, v47
	v_add_f32_e32 v0, v66, v0
	v_add_f32_e32 v0, v67, v0
	v_add_f32_e32 v0, v68, v0
	v_add_f32_e32 v0, v69, v0
	v_add_f32_e32 v0, v70, v0
	global_store_dwordx4 v[72:73], v[104:107], off offset:3072
	v_pk_mul_f32 v[72:73], v[100:101], v[100:101]
	v_add_f32_e32 v0, v71, v0
	v_add_f32_e32 v0, v72, v0
	v_add_f32_e32 v0, v73, v0
	v_add_f32_e32 v0, v74, v0
	v_pk_mul_f32 v[76:77], v[104:105], v[104:105]
	v_add_f32_e32 v0, v75, v0
	v_add_f32_e32 v0, v76, v0
	v_pk_mul_f32 v[78:79], v[106:107], v[106:107]
	v_add_f32_e32 v0, v77, v0
	v_add_f32_e32 v0, v78, v0
	v_add_f32_e32 v0, v79, v0
	ds_bpermute_b32 v35, v48, v0
	s_waitcnt lgkmcnt(0)
	v_add_f32_e32 v0, v0, v35
	ds_bpermute_b32 v35, v49, v0
	s_waitcnt lgkmcnt(0)
	v_add_f32_e32 v0, v0, v35
	ds_bpermute_b32 v35, v50, v0
	s_waitcnt lgkmcnt(0)
	v_add_f32_e32 v0, v0, v35
	ds_bpermute_b32 v35, v51, v0
	s_waitcnt lgkmcnt(0)
	v_add_f32_e32 v0, v0, v35
	ds_bpermute_b32 v35, v52, v0
	s_waitcnt lgkmcnt(0)
	v_add_f32_e32 v0, v0, v35
	ds_bpermute_b32 v35, v53, v0
	s_waitcnt lgkmcnt(0)
	v_add_f32_e32 v0, v0, v35
	v_fmamk_f32 v0, v0, 0x3a800000, v174
	v_cmp_gt_f32_e32 vcc, s8, v0
	v_mul_f32_e32 v35, 0x4b800000, v0
	s_movk_i32 s8, 0x403f
	v_cndmask_b32_e32 v0, v0, v35, vcc
	v_rsq_f32_e32 v0, v0
	s_nop 0
	v_mul_f32_e32 v35, 0x45800000, v0
	v_cndmask_b32_e32 v0, v0, v35, vcc
	v_pk_mul_f32 v[42:43], v[42:43], v[0:1] op_sel_hi:[1,0]
	v_pk_mul_f32 v[44:45], v[44:45], v[0:1] op_sel_hi:[1,0]
	v_pk_mul_f32 v[42:43], v[14:15], v[42:43]
	v_pk_mul_f32 v[44:45], v[16:17], v[44:45]
	v_cvt_pk_bf16_f32 v42, v42, v43
	v_cvt_pk_bf16_f32 v43, v44, v45
	global_store_dwordx2 v[40:41], v[42:43], off
	v_pk_mul_f32 v[42:43], v[96:97], v[0:1] op_sel_hi:[1,0]
	v_pk_mul_f32 v[44:45], v[98:99], v[0:1] op_sel_hi:[1,0]
	v_pk_mul_f32 v[42:43], v[22:23], v[42:43]
	v_pk_mul_f32 v[44:45], v[24:25], v[44:45]
	v_cvt_pk_bf16_f32 v42, v42, v43
	v_cvt_pk_bf16_f32 v43, v44, v45
	global_store_dwordx2 v[40:41], v[42:43], off offset:512
	v_pk_mul_f32 v[42:43], v[100:101], v[0:1] op_sel_hi:[1,0]
	v_pk_mul_f32 v[44:45], v[102:103], v[0:1] op_sel_hi:[1,0]
	v_pk_mul_f32 v[42:43], v[42:43], v[26:27]
	v_pk_mul_f32 v[44:45], v[44:45], v[28:29]
	v_cvt_pk_bf16_f32 v42, v42, v43
	v_cvt_pk_bf16_f32 v43, v44, v45
	global_store_dwordx2 v[40:41], v[42:43], off offset:1024
	v_pk_mul_f32 v[42:43], v[104:105], v[0:1] op_sel_hi:[1,0]
	v_pk_mul_f32 v[44:45], v[106:107], v[0:1] op_sel_hi:[1,0]
	v_pk_mul_f32 v[42:43], v[42:43], v[30:31]
	v_pk_mul_f32 v[44:45], v[44:45], v[32:33]
	v_cmp_lt_i32_e32 vcc, s8, v34
	v_cvt_pk_bf16_f32 v42, v42, v43
	v_cvt_pk_bf16_f32 v43, v44, v45
	s_or_b64 s[4:5], vcc, s[4:5]
	global_store_dwordx2 v[40:41], v[42:43], off offset:1536
	s_andn2_b64 exec, exec, s[4:5]
	s_cbranch_execz .LBB0_982

; __device__ __forceinline__ int otid() { int t = threadIdx.x; asm volatile("" : "+v"(t)); return t; }
; __device__ __forceinline__ void rowpass_resid(const Params& p, const float* __restrict__ ga, const float* __restrict__ gb, bool write_xn, bool from_x = false) {
;     const int tid_ = otid(); const int lane = tid_ & 63, w = tid_ >> 6;
;     bf16_t* XU = (bf16_t*)(p.ws + OFF_XU);
;     for (int row = blockIdx.x * 8 + w; row < T; row += gridDim.x * 8) {
;         float* hp = hrow(p, row);
;         const float* hsrc = hp;
;         if (from_x) { const int b_ = row / L, pos_ = row - b_ * L; if (pos_ >= NMETA) hsrc = p.in[0] + ((size_t)b_ * SEQ + pos_ - NMETA) * DM; }
;         bf16_t* xp = XU + (size_t)row * DM;
;     ...
; #pragma unroll
;             for (int i = 0; i < 4; ++i) {
;                 float4 g4 = *(const float4*)(gb + lane * 4 + 256 * i);
.LBB0_1208:
	s_or_b64 exec, exec, s[0:1]
	v_mov_b32_e32 v0, v166
	s_barrier
	v_readlane_b32 s0, v252, 39
	v_ashrrev_i32_e32 v2, 6, v0
	s_nop 0
	v_add_u32_e32 v34, s0, v2
	s_movk_i32 s0, 0x4040
	v_cmp_gt_i32_e32 vcc, s0, v34
	s_and_saveexec_b64 s[2:3], vcc
	s_cbranch_execz .LBB0_1217
	v_lshlrev_b32_e32 v0, 2, v0
	v_and_b32_e32 v18, 0xfc, v0
	v_lshlrev_b32_e32 v0, 2, v18
	v_lshl_add_u64 v[20:21], s[6:7], 0, v[0:1]
	s_mov_b64 s[0:1], 0x3000
	v_lshl_add_u64 v[14:15], v[20:21], 0, s[0:1]
	s_movk_i32 s0, 0x3000
	v_add_co_u32_e32 v10, vcc, s0, v20
	v_and_b32_e32 v0, 64, v183
	s_nop 0
	v_addc_co_u32_e32 v11, vcc, 0, v21, vcc
	global_load_dwordx4 v[2:5], v[14:15], off offset:1024
	global_load_dwordx4 v[6:9], v[14:15], off offset:2048
	s_nop 0
	global_load_dwordx4 v[10:13], v[10:11], off
	s_nop 0
	global_load_dwordx4 v[14:17], v[14:15], off offset:3072
	v_add_u32_e32 v0, 64, v0
	v_xor_b32_e32 v19, 32, v183
	v_cmp_lt_i32_e32 vcc, v19, v0
	s_mov_b64 s[0:1], 0x4000
	v_lshl_add_u64 v[36:37], v[20:21], 0, s[0:1]
	v_cndmask_b32_e32 v19, v183, v19, vcc
	v_lshlrev_b32_e32 v44, 2, v19
	v_xor_b32_e32 v19, 16, v183
	v_cmp_lt_i32_e32 vcc, v19, v0
	s_mov_b64 s[6:7], 0
	s_nop 0
	v_cndmask_b32_e32 v19, v183, v19, vcc
	v_lshlrev_b32_e32 v45, 2, v19
	v_xor_b32_e32 v19, 8, v183
	v_cmp_lt_i32_e32 vcc, v19, v0
	s_nop 1
	v_cndmask_b32_e32 v19, v183, v19, vcc
	v_lshlrev_b32_e32 v46, 2, v19
	v_xor_b32_e32 v19, 4, v183
	v_cmp_lt_i32_e32 vcc, v19, v0
	s_nop 1
	v_cndmask_b32_e32 v19, v183, v19, vcc
	v_lshlrev_b32_e32 v47, 2, v19
	v_xor_b32_e32 v19, 2, v183
	v_cmp_lt_i32_e32 vcc, v19, v0
	s_nop 1
	v_cndmask_b32_e32 v19, v183, v19, vcc
	v_lshlrev_b32_e32 v48, 2, v19
	v_xor_b32_e32 v19, 1, v183
	v_cmp_lt_i32_e32 vcc, v19, v0
	s_nop 1
	v_cndmask_b32_e32 v0, v183, v19, vcc
	v_lshlrev_b32_e32 v49, 2, v0
	v_lshlrev_b32_e32 v0, 1, v18
	v_lshl_add_u64 v[38:39], s[90:91], 0, v[0:1]
	v_lshlrev_b32_e32 v0, 2, v18
	s_and_b64 vcc, exec, s[4:5]
	s_cbranch_vccnz .Lresid2_nogb
	global_load_dwordx4 v[84:87], v[36:37], off
	global_load_dwordx4 v[88:91], v[36:37], off offset:1024
	global_load_dwordx4 v[92:95], v[36:37], off offset:2048
	global_load_dwordx4 v[96:99], v[36:37], off offset:3072
.Lresid2_nogb:
	s_branch .LBB0_1211
.LBB0_1210:
	v_add_u32_e32 v34, s66, v34
	s_movk_i32 s0, 0x403f
	v_cmp_lt_i32_e32 vcc, s0, v34
	s_or_b64 s[6:7], vcc, s[6:7]
	s_andn2_b64 exec, exec, s[6:7]
	s_cbranch_execz .LBB0_1217

; __device__ __forceinline__ float bf2f(bf16_t h) { return __uint_as_float(((unsigned)h) << 16); }
; __device__ __forceinline__ void rowpass_resid(const Params& p, const float* __restrict__ ga, const float* __restrict__ gb, bool write_xn, bool from_x = false) {
;     ...
;         float* hp = hrow(p, row);
;         const float* hsrc = hp;
;         if (from_x) { const int b_ = row / L, pos_ = row - b_ * L; if (pos_ >= NMETA) hsrc = p.in[0] + ((size_t)b_ * SEQ + pos_ - NMETA) * DM; }
;         bf16_t* xp = XU + (size_t)row * DM;
;         float u[16]; float ss = 0.f;
; #pragma unroll
;         for (int i = 0; i < 4; ++i) {
;             uint2 q = *(const uint2*)(xp + lane * 4 + 256 * i);
;             u[4 * i + 0] = bf2f((bf16_t)(q.x & 0xFFFF)); u[4 * i + 1] = bf2f((bf16_t)(q.x >> 16));
;             u[4 * i + 2] = bf2f((bf16_t)(q.y & 0xFFFF)); u[4 * i + 3] = bf2f((bf16_t)(q.y >> 16));
; #pragma unroll
;             for (int j = 0; j < 4; ++j) ss += u[4 * i + j] * u[4 * i + j];
;         }
;         ss = wave_sum(ss);
;         float r = rsqrtf(ss * (1.0f / DM) + EPS);
;         float hv[16]; float s2 = 0.f;
; #pragma unroll
;         for (int i = 0; i < 4; ++i) {
;             float4 h4 = *(const float4*)(hsrc + lane * 4 + 256 * i);
;             float4 g4 = *(const float4*)(ga + lane * 4 + 256 * i);
;             hv[4 * i + 0] = h4.x + u[4 * i + 0] * r * g4.x;
;             hv[4 * i + 1] = h4.y + u[4 * i + 1] * r * g4.y;
;             hv[4 * i + 2] = h4.z + u[4 * i + 2] * r * g4.z;
;             hv[4 * i + 3] = h4.w + u[4 * i + 3] * r * g4.w;
;             *(float4*)(hp + lane * 4 + 256 * i) = make_float4(hv[4 * i], hv[4 * i + 1], hv[4 * i + 2], hv[4 * i + 3]);
; #pragma unroll
;             for (int j = 0; j < 4; ++j) s2 += hv[4 * i + j] * hv[4 * i + j];
;         }
;         if (write_xn) {
;             s2 = wave_sum(s2);
;             float r2 = rsqrtf(s2 * (1.0f / DM) + EPS);
; #pragma unroll
;             for (int i = 0; i < 4; ++i) {
;                 float4 g4 = *(const float4*)(gb + lane * 4 + 256 * i);
;                 uint2 o; o.x = pack2(hv[4 * i] * r2 * g4.x, hv[4 * i + 1] * r2 * g4.y);
;                 o.y = pack2(hv[4 * i + 2] * r2 * g4.z, hv[4 * i + 3] * r2 * g4.w);
;                 *(uint2*)(xp + lane * 4 + 256 * i) = o;
;             }
.LBB0_1215:
	s_or_b64 exec, exec, s[0:1]
	v_ashrrev_i32_e32 v35, 31, v34
	v_lshlrev_b64 v[22:23], 11, v[34:35]
	v_lshl_add_u64 v[40:41], v[38:39], 0, v[22:23]
	global_load_dwordx2 v[26:27], v[40:41], off
	global_load_dwordx2 v[28:29], v[40:41], off offset:512
	global_load_dwordx2 v[30:31], v[40:41], off offset:1024
	global_load_dwordx2 v[32:33], v[40:41], off offset:1536
	v_lshlrev_b64 v[18:19], 12, v[18:19]
	v_lshl_add_u64 v[18:19], v[20:21], 0, v[18:19]
	v_lshl_add_u64 v[58:59], v[18:19], 0, v[0:1]
	global_load_dwordx4 v[18:21], v[58:59], off
	global_load_dwordx4 v[22:25], v[58:59], off offset:1024
	global_load_dwordx4 v[50:53], v[58:59], off offset:2048
	global_load_dwordx4 v[54:57], v[58:59], off offset:3072
	s_mov_b32 s0, 0x800000
	s_and_b64 vcc, exec, s[4:5]
	s_waitcnt vmcnt(7)
	v_lshlrev_b32_e32 v60, 16, v26
	v_and_b32_e32 v61, 0xffff0000, v26
	v_lshlrev_b32_e32 v26, 16, v27
	v_and_b32_e32 v27, 0xffff0000, v27
	v_pk_mul_f32 v[70:71], v[60:61], v[60:61]
	v_pk_mul_f32 v[68:69], v[26:27], v[26:27]
	v_add_f32_e32 v35, v70, v71
	s_waitcnt vmcnt(6)
	v_lshlrev_b32_e32 v62, 16, v28
	v_and_b32_e32 v63, 0xffff0000, v28
	v_add_f32_e32 v35, v35, v68
	v_pk_mul_f32 v[74:75], v[62:63], v[62:63]
	v_add_f32_e32 v35, v69, v35
	v_lshlrev_b32_e32 v28, 16, v29
	v_and_b32_e32 v29, 0xffff0000, v29
	v_add_f32_e32 v35, v74, v35
	v_pk_mul_f32 v[72:73], v[28:29], v[28:29]
	v_add_f32_e32 v35, v75, v35
	s_waitcnt vmcnt(5)
	v_lshlrev_b32_e32 v64, 16, v30
	v_and_b32_e32 v65, 0xffff0000, v30
	v_add_f32_e32 v35, v72, v35
	v_pk_mul_f32 v[78:79], v[64:65], v[64:65]
	v_add_f32_e32 v35, v73, v35
	v_lshlrev_b32_e32 v30, 16, v31
	v_and_b32_e32 v31, 0xffff0000, v31
	v_add_f32_e32 v35, v78, v35
	v_pk_mul_f32 v[76:77], v[30:31], v[30:31]
	v_add_f32_e32 v35, v79, v35
	s_waitcnt vmcnt(4)
	v_lshlrev_b32_e32 v66, 16, v32
	v_and_b32_e32 v67, 0xffff0000, v32
	v_add_f32_e32 v35, v76, v35
	v_pk_mul_f32 v[82:83], v[66:67], v[66:67]
	v_add_f32_e32 v35, v77, v35
	v_lshlrev_b32_e32 v32, 16, v33
	v_and_b32_e32 v33, 0xffff0000, v33
	v_add_f32_e32 v35, v82, v35
	v_pk_mul_f32 v[80:81], v[32:33], v[32:33]
	v_add_f32_e32 v35, v83, v35
	v_add_f32_e32 v35, v80, v35
	v_add_f32_e32 v35, v81, v35
	ds_bpermute_b32 v42, v44, v35
	s_waitcnt lgkmcnt(0)
	v_add_f32_e32 v35, v35, v42
	ds_bpermute_b32 v42, v45, v35
	s_waitcnt lgkmcnt(0)
	v_add_f32_e32 v35, v35, v42
	ds_bpermute_b32 v42, v46, v35
	s_waitcnt lgkmcnt(0)
	v_add_f32_e32 v35, v35, v42
	ds_bpermute_b32 v42, v47, v35
	s_waitcnt lgkmcnt(0)
	v_add_f32_e32 v35, v35, v42
	ds_bpermute_b32 v42, v48, v35
	s_waitcnt lgkmcnt(0)
	v_add_f32_e32 v35, v35, v42
	ds_bpermute_b32 v42, v49, v35
	s_waitcnt lgkmcnt(0)
	v_add_f32_e32 v35, v35, v42
	v_fmamk_f32 v35, v35, 0x3a800000, v174
	v_mul_f32_e32 v42, 0x4b800000, v35
	v_cmp_gt_f32_e64 s[0:1], s0, v35
	s_nop 1
	v_cndmask_b32_e64 v35, v35, v42, s[0:1]
	v_rsq_f32_e32 v35, v35
	s_nop 0
	v_mul_f32_e32 v42, 0x45800000, v35
	v_cndmask_b32_e64 v42, v35, v42, s[0:1]
	v_pk_mul_f32 v[60:61], v[42:43], v[60:61] op_sel_hi:[0,1]
	v_pk_mul_f32 v[26:27], v[42:43], v[26:27] op_sel_hi:[0,1]
	v_pk_mul_f32 v[62:63], v[42:43], v[62:63] op_sel_hi:[0,1]
	v_pk_mul_f32 v[28:29], v[42:43], v[28:29] op_sel_hi:[0,1]
	v_pk_mul_f32 v[64:65], v[42:43], v[64:65] op_sel_hi:[0,1]
	v_pk_mul_f32 v[68:69], v[42:43], v[30:31] op_sel_hi:[0,1]
	v_pk_mul_f32 v[66:67], v[42:43], v[66:67] op_sel_hi:[0,1]
	v_pk_mul_f32 v[70:71], v[42:43], v[32:33] op_sel_hi:[0,1]
	s_waitcnt vmcnt(3)
	v_pk_fma_f32 v[30:31], v[10:11], v[60:61], v[18:19]
	v_pk_fma_f32 v[32:33], v[12:13], v[26:27], v[20:21]
	s_waitcnt vmcnt(2)
	v_pk_fma_f32 v[26:27], v[2:3], v[62:63], v[22:23]
	v_pk_fma_f32 v[28:29], v[4:5], v[28:29], v[24:25]
	s_waitcnt vmcnt(1)
	v_pk_fma_f32 v[22:23], v[6:7], v[64:65], v[50:51]
	v_pk_fma_f32 v[24:25], v[8:9], v[68:69], v[52:53]
	s_waitcnt vmcnt(0)
	v_pk_fma_f32 v[18:19], v[14:15], v[66:67], v[54:55]
	v_pk_fma_f32 v[20:21], v[16:17], v[70:71], v[56:57]
	global_store_dwordx4 v[58:59], v[30:33], off
	global_store_dwordx4 v[58:59], v[26:29], off offset:1024
	global_store_dwordx4 v[58:59], v[22:25], off offset:2048
	global_store_dwordx4 v[58:59], v[18:21], off offset:3072
	s_cbranch_vccnz .LBB0_1210
	v_pk_mul_f32 v[50:51], v[30:31], v[30:31]
	v_pk_mul_f32 v[52:53], v[32:33], v[32:33]
	v_add_f32_e32 v35, v50, v51
	v_add_f32_e32 v35, v52, v35
	v_add_f32_e32 v35, v53, v35
	v_pk_mul_f32 v[54:55], v[26:27], v[26:27]
	v_pk_mul_f32 v[56:57], v[28:29], v[28:29]
	v_add_f32_e32 v35, v54, v35
	v_add_f32_e32 v35, v55, v35
	v_add_f32_e32 v35, v56, v35
	v_pk_mul_f32 v[58:59], v[22:23], v[22:23]
	v_add_f32_e32 v35, v57, v35
	v_add_f32_e32 v35, v58, v35
	v_pk_mul_f32 v[60:61], v[24:25], v[24:25]
	v_add_f32_e32 v35, v59, v35
	v_add_f32_e32 v35, v60, v35
	v_pk_mul_f32 v[62:63], v[18:19], v[18:19]
	v_add_f32_e32 v35, v61, v35
	v_add_f32_e32 v35, v62, v35
	v_pk_mul_f32 v[64:65], v[20:21], v[20:21]
	v_add_f32_e32 v35, v63, v35
	v_add_f32_e32 v35, v64, v35
	v_add_f32_e32 v35, v65, v35
	ds_bpermute_b32 v42, v44, v35
	s_mov_b32 s0, 0x800000
	s_waitcnt lgkmcnt(0)
	v_add_f32_e32 v35, v35, v42
	ds_bpermute_b32 v42, v45, v35
	s_waitcnt lgkmcnt(0)
	v_add_f32_e32 v35, v35, v42
	ds_bpermute_b32 v42, v46, v35
	s_waitcnt lgkmcnt(0)
	v_add_f32_e32 v35, v35, v42
	ds_bpermute_b32 v42, v47, v35
	s_waitcnt lgkmcnt(0)
	v_add_f32_e32 v35, v35, v42
	ds_bpermute_b32 v42, v48, v35
	s_waitcnt lgkmcnt(0)
	v_add_f32_e32 v35, v35, v42
	ds_bpermute_b32 v42, v49, v35
	s_waitcnt lgkmcnt(0)
	v_add_f32_e32 v35, v35, v42
	v_fmamk_f32 v35, v35, 0x3a800000, v174
	v_cmp_gt_f32_e32 vcc, s0, v35
	v_mul_f32_e32 v42, 0x4b800000, v35
	s_nop 0
	v_cndmask_b32_e32 v35, v35, v42, vcc
	v_rsq_f32_e32 v35, v35
	s_nop 0
	v_mul_f32_e32 v42, 0x45800000, v35
	v_cndmask_b32_e32 v42, v35, v42, vcc
	v_pk_mul_f32 v[30:31], v[30:31], v[42:43] op_sel_hi:[1,0]
	v_pk_mul_f32 v[32:33], v[32:33], v[42:43] op_sel_hi:[1,0]
	v_pk_mul_f32 v[26:27], v[26:27], v[42:43] op_sel_hi:[1,0]
	v_pk_mul_f32 v[28:29], v[28:29], v[42:43] op_sel_hi:[1,0]
	v_pk_mul_f32 v[22:23], v[22:23], v[42:43] op_sel_hi:[1,0]
	v_pk_mul_f32 v[24:25], v[24:25], v[42:43] op_sel_hi:[1,0]
	v_pk_mul_f32 v[18:19], v[18:19], v[42:43] op_sel_hi:[1,0]
	v_pk_mul_f32 v[20:21], v[20:21], v[42:43] op_sel_hi:[1,0]
	v_pk_mul_f32 v[30:31], v[84:85], v[30:31]
	v_pk_mul_f32 v[32:33], v[86:87], v[32:33]
	v_cvt_pk_bf16_f32 v30, v30, v31
	v_cvt_pk_bf16_f32 v31, v32, v33
	global_store_dwordx2 v[40:41], v[30:31], off
	v_pk_mul_f32 v[26:27], v[88:89], v[26:27]
	v_pk_mul_f32 v[28:29], v[90:91], v[28:29]
	v_cvt_pk_bf16_f32 v26, v26, v27
	v_cvt_pk_bf16_f32 v27, v28, v29
	global_store_dwordx2 v[40:41], v[26:27], off offset:512
	v_pk_mul_f32 v[22:23], v[22:23], v[92:93]
	v_pk_mul_f32 v[24:25], v[24:25], v[94:95]
	v_cvt_pk_bf16_f32 v22, v22, v23
	v_cvt_pk_bf16_f32 v23, v24, v25
	global_store_dwordx2 v[40:41], v[22:23], off offset:1024
	v_pk_mul_f32 v[18:19], v[18:19], v[96:97]
	v_pk_mul_f32 v[20:21], v[20:21], v[98:99]
	v_cvt_pk_bf16_f32 v18, v18, v19
	v_cvt_pk_bf16_f32 v19, v20, v21
	global_store_dwordx2 v[40:41], v[18:19], off offset:1536
	s_branch .LBB0_1210
